# attn FAST epilogue: O tile staged via private per-wave LDS region and stored with 8 dwordx4 instead of 64 short stores
# baseline (speedup 1.0000x reference)
.LBB0_420:
	s_or_b64 exec, exec, s[6:7]
	s_waitcnt lgkmcnt(0)
	v_lshl_add_u32 v1, v71, 4, s3
	ds_read_b128 v[66:69], v1
	ds_read_b128 v[72:75], v1 offset:32
	ds_read_b128 v[76:79], v1 offset:64
	ds_read_b128 v[80:83], v1 offset:96
	s_lshl_b32 s8, s53, 12
	s_lshl_b64 s[6:7], s[50:51], 25
	s_or_b32 s6, s6, s8
	s_add_u32 s6, s34, s6
	s_addc_u32 s3, s35, s7
	s_add_u32 s6, s6, s54
	s_addc_u32 s7, s3, 0
	s_lshl_b32 s2, s2, 5
	s_ashr_i32 s3, s2, 31
	s_lshl_b64 s[2:3], s[2:3], 12
	s_add_u32 s2, s6, s2
	s_addc_u32 s3, s7, s3
	s_and_b32 s8, s55, 0x3c0
	s_lshl_b32 s8, s8, 7
	s_add_i32 s8, s8, 0x11000
	v_lshlrev_b32_e32 v84, 10, v71
	v_lshl_add_u32 v84, v70, 1, v84
	v_add_u32_e32 v84, s8, v84
	v_lshl_or_b32 v86, v71, 5, v70
	v_lshrrev_b32_e32 v87, 4, v86
	v_and_b32_e32 v86, 15, v86
	v_lshlrev_b32_e32 v85, 8, v87
	v_lshl_add_u32 v85, v86, 4, v85
	v_add_u32_e32 v85, s8, v85
	v_lshlrev_b32_e32 v88, 12, v87
	v_lshl_add_u32 v88, v86, 4, v88
	v_mov_b32_e32 v89, v114
	v_lshl_add_u64 v[88:89], s[2:3], 0, v[88:89]
	s_waitcnt lgkmcnt(0)
	v_rcp_f32_e32 v66, v66
	v_rcp_f32_e32 v67, v67
	v_rcp_f32_e32 v68, v68
	v_rcp_f32_e32 v69, v69
	v_rcp_f32_e32 v72, v72
	v_rcp_f32_e32 v73, v73
	v_rcp_f32_e32 v74, v74
	v_rcp_f32_e32 v75, v75
	v_rcp_f32_e32 v76, v76
	v_rcp_f32_e32 v77, v77
	v_rcp_f32_e32 v78, v78
	v_rcp_f32_e32 v79, v79
	v_rcp_f32_e32 v80, v80
	v_rcp_f32_e32 v81, v81
	v_rcp_f32_e32 v82, v82
	v_rcp_f32_e32 v83, v83
	s_nop 0
	v_mul_f32_e32 v90, v2, v66
	v_mul_f32_e32 v91, v18, v66
	v_mul_f32_e32 v92, v34, v66
	v_mul_f32_e32 v93, v50, v66
	v_cvt_pk_bf16_f32 v90, v90, v91
	v_cvt_pk_bf16_f32 v92, v92, v93
	ds_write_b16 v84, v90 offset:0
	ds_write_b16_d16_hi v84, v90 offset:64
	ds_write_b16 v84, v92 offset:128
	ds_write_b16_d16_hi v84, v92 offset:192
	v_mul_f32_e32 v94, v3, v67
	v_mul_f32_e32 v95, v19, v67
	v_mul_f32_e32 v96, v35, v67
	v_mul_f32_e32 v97, v51, v67
	v_cvt_pk_bf16_f32 v94, v94, v95
	v_cvt_pk_bf16_f32 v96, v96, v97
	ds_write_b16 v84, v94 offset:256
	ds_write_b16_d16_hi v84, v94 offset:320
	ds_write_b16 v84, v96 offset:384
	ds_write_b16_d16_hi v84, v96 offset:448
	v_mul_f32_e32 v98, v4, v68
	v_mul_f32_e32 v99, v20, v68
	v_mul_f32_e32 v100, v36, v68
	v_mul_f32_e32 v101, v52, v68
	v_cvt_pk_bf16_f32 v98, v98, v99
	v_cvt_pk_bf16_f32 v100, v100, v101
	ds_write_b16 v84, v98 offset:512
	ds_write_b16_d16_hi v84, v98 offset:576
	ds_write_b16 v84, v100 offset:640
	ds_write_b16_d16_hi v84, v100 offset:704
	v_mul_f32_e32 v102, v5, v69
	v_mul_f32_e32 v103, v21, v69
	v_mul_f32_e32 v104, v37, v69
	v_mul_f32_e32 v105, v53, v69
	v_cvt_pk_bf16_f32 v102, v102, v103
	v_cvt_pk_bf16_f32 v104, v104, v105
	ds_write_b16 v84, v102 offset:768
	ds_write_b16_d16_hi v84, v102 offset:832
	ds_write_b16 v84, v104 offset:896
	ds_write_b16_d16_hi v84, v104 offset:960
	v_mul_f32_e32 v90, v6, v72
	v_mul_f32_e32 v91, v22, v72
	v_mul_f32_e32 v92, v38, v72
	v_mul_f32_e32 v93, v54, v72
	v_cvt_pk_bf16_f32 v90, v90, v91
	v_cvt_pk_bf16_f32 v92, v92, v93
	ds_write_b16 v84, v90 offset:2048
	ds_write_b16_d16_hi v84, v90 offset:2112
	ds_write_b16 v84, v92 offset:2176
	ds_write_b16_d16_hi v84, v92 offset:2240
	v_mul_f32_e32 v94, v7, v73
	v_mul_f32_e32 v95, v23, v73
	v_mul_f32_e32 v96, v39, v73
	v_mul_f32_e32 v97, v55, v73
	v_cvt_pk_bf16_f32 v94, v94, v95
	v_cvt_pk_bf16_f32 v96, v96, v97
	ds_write_b16 v84, v94 offset:2304
	ds_write_b16_d16_hi v84, v94 offset:2368
	ds_write_b16 v84, v96 offset:2432
	ds_write_b16_d16_hi v84, v96 offset:2496
	v_mul_f32_e32 v98, v8, v74
	v_mul_f32_e32 v99, v24, v74
	v_mul_f32_e32 v100, v40, v74
	v_mul_f32_e32 v101, v56, v74
	v_cvt_pk_bf16_f32 v98, v98, v99
	v_cvt_pk_bf16_f32 v100, v100, v101
	ds_write_b16 v84, v98 offset:2560
	ds_write_b16_d16_hi v84, v98 offset:2624
	ds_write_b16 v84, v100 offset:2688
	ds_write_b16_d16_hi v84, v100 offset:2752
	v_mul_f32_e32 v102, v9, v75
	v_mul_f32_e32 v103, v25, v75
	v_mul_f32_e32 v104, v41, v75
	v_mul_f32_e32 v105, v57, v75
	v_cvt_pk_bf16_f32 v102, v102, v103
	v_cvt_pk_bf16_f32 v104, v104, v105
	ds_write_b16 v84, v102 offset:2816
	ds_write_b16_d16_hi v84, v102 offset:2880
	ds_write_b16 v84, v104 offset:2944
	ds_write_b16_d16_hi v84, v104 offset:3008
	v_mul_f32_e32 v90, v10, v76
	v_mul_f32_e32 v91, v26, v76
	v_mul_f32_e32 v92, v42, v76
	v_mul_f32_e32 v93, v58, v76
	v_cvt_pk_bf16_f32 v90, v90, v91
	v_cvt_pk_bf16_f32 v92, v92, v93
	ds_write_b16 v84, v90 offset:4096
	ds_write_b16_d16_hi v84, v90 offset:4160
	ds_write_b16 v84, v92 offset:4224
	ds_write_b16_d16_hi v84, v92 offset:4288
	v_mul_f32_e32 v94, v11, v77
	v_mul_f32_e32 v95, v27, v77
	v_mul_f32_e32 v96, v43, v77
	v_mul_f32_e32 v97, v59, v77
	v_cvt_pk_bf16_f32 v94, v94, v95
	v_cvt_pk_bf16_f32 v96, v96, v97
	ds_write_b16 v84, v94 offset:4352
	ds_write_b16_d16_hi v84, v94 offset:4416
	ds_write_b16 v84, v96 offset:4480
	ds_write_b16_d16_hi v84, v96 offset:4544
	v_mul_f32_e32 v98, v12, v78
	v_mul_f32_e32 v99, v28, v78
	v_mul_f32_e32 v100, v44, v78
	v_mul_f32_e32 v101, v60, v78
	v_cvt_pk_bf16_f32 v98, v98, v99
	v_cvt_pk_bf16_f32 v100, v100, v101
	ds_write_b16 v84, v98 offset:4608
	ds_write_b16_d16_hi v84, v98 offset:4672
	ds_write_b16 v84, v100 offset:4736
	ds_write_b16_d16_hi v84, v100 offset:4800
	v_mul_f32_e32 v102, v13, v79
	v_mul_f32_e32 v103, v29, v79
	v_mul_f32_e32 v104, v45, v79
	v_mul_f32_e32 v105, v61, v79
	v_cvt_pk_bf16_f32 v102, v102, v103
	v_cvt_pk_bf16_f32 v104, v104, v105
	ds_write_b16 v84, v102 offset:4864
	ds_write_b16_d16_hi v84, v102 offset:4928
	ds_write_b16 v84, v104 offset:4992
	ds_write_b16_d16_hi v84, v104 offset:5056
	v_mul_f32_e32 v90, v14, v80
	v_mul_f32_e32 v91, v30, v80
	v_mul_f32_e32 v92, v46, v80
	v_mul_f32_e32 v93, v62, v80
	v_cvt_pk_bf16_f32 v90, v90, v91
	v_cvt_pk_bf16_f32 v92, v92, v93
	ds_write_b16 v84, v90 offset:6144
	ds_write_b16_d16_hi v84, v90 offset:6208
	ds_write_b16 v84, v92 offset:6272
	ds_write_b16_d16_hi v84, v92 offset:6336
	v_mul_f32_e32 v94, v15, v81
	v_mul_f32_e32 v95, v31, v81
	v_mul_f32_e32 v96, v47, v81
	v_mul_f32_e32 v97, v63, v81
	v_cvt_pk_bf16_f32 v94, v94, v95
	v_cvt_pk_bf16_f32 v96, v96, v97
	ds_write_b16 v84, v94 offset:6400
	ds_write_b16_d16_hi v84, v94 offset:6464
	ds_write_b16 v84, v96 offset:6528
	ds_write_b16_d16_hi v84, v96 offset:6592
	v_mul_f32_e32 v98, v16, v82
	v_mul_f32_e32 v99, v32, v82
	v_mul_f32_e32 v100, v48, v82
	v_mul_f32_e32 v101, v64, v82
	v_cvt_pk_bf16_f32 v98, v98, v99
	v_cvt_pk_bf16_f32 v100, v100, v101
	ds_write_b16 v84, v98 offset:6656
	ds_write_b16_d16_hi v84, v98 offset:6720
	ds_write_b16 v84, v100 offset:6784
	ds_write_b16_d16_hi v84, v100 offset:6848
	v_mul_f32_e32 v102, v17, v83
	v_mul_f32_e32 v103, v33, v83
	v_mul_f32_e32 v104, v49, v83
	v_mul_f32_e32 v105, v65, v83
	v_cvt_pk_bf16_f32 v102, v102, v103
	v_cvt_pk_bf16_f32 v104, v104, v105
	ds_write_b16 v84, v102 offset:6912
	ds_write_b16_d16_hi v84, v102 offset:6976
	ds_write_b16 v84, v104 offset:7040
	ds_write_b16_d16_hi v84, v104 offset:7104
	s_waitcnt lgkmcnt(0)
	ds_read_b128 v[116:119], v85 offset:0
	ds_read_b128 v[120:123], v85 offset:1024
	ds_read_b128 v[124:127], v85 offset:2048
	ds_read_b128 v[128:131], v85 offset:3072
	ds_read_b128 v[132:135], v85 offset:4096
	ds_read_b128 v[136:139], v85 offset:5120
	ds_read_b128 v[140:143], v85 offset:6144
	ds_read_b128 v[144:147], v85 offset:7168
	s_mov_b32 s8, 0x4000
	s_waitcnt lgkmcnt(7)
	global_store_dwordx4 v[88:89], v[116:119], off
	v_add_co_u32_e32 v88, vcc, s8, v88
	s_nop 1
	v_addc_co_u32_e32 v89, vcc, 0, v89, vcc
	s_waitcnt lgkmcnt(6)
	global_store_dwordx4 v[88:89], v[120:123], off
	v_add_co_u32_e32 v88, vcc, s8, v88
	s_nop 1
	v_addc_co_u32_e32 v89, vcc, 0, v89, vcc
	s_waitcnt lgkmcnt(5)
	global_store_dwordx4 v[88:89], v[124:127], off
	v_add_co_u32_e32 v88, vcc, s8, v88
	s_nop 1
	v_addc_co_u32_e32 v89, vcc, 0, v89, vcc
	s_waitcnt lgkmcnt(4)
	global_store_dwordx4 v[88:89], v[128:131], off
	v_add_co_u32_e32 v88, vcc, s8, v88
	s_nop 1
	v_addc_co_u32_e32 v89, vcc, 0, v89, vcc
	s_waitcnt lgkmcnt(3)
	global_store_dwordx4 v[88:89], v[132:135], off
	v_add_co_u32_e32 v88, vcc, s8, v88
	s_nop 1
	v_addc_co_u32_e32 v89, vcc, 0, v89, vcc
	s_waitcnt lgkmcnt(2)
	global_store_dwordx4 v[88:89], v[136:139], off
	v_add_co_u32_e32 v88, vcc, s8, v88
	s_nop 1
	v_addc_co_u32_e32 v89, vcc, 0, v89, vcc
	s_waitcnt lgkmcnt(1)
	global_store_dwordx4 v[88:89], v[140:143], off
	v_add_co_u32_e32 v88, vcc, s8, v88
	s_nop 1
	v_addc_co_u32_e32 v89, vcc, 0, v89, vcc
	s_waitcnt lgkmcnt(0)
	global_store_dwordx4 v[88:89], v[144:147], off
	s_add_i32 s52, s52, 1
	s_mov_b64 s[6:7], 0
	s_barrier
